# both GEMM main loops (loop-edge): loop-exit compare issued behind the last segment's MFMAs, only the branch follows the closing barrier
# baseline (speedup 1.0000x reference)
.LBB0_630:
	s_ashr_i32 s85, s84, 31
	s_lshl_b64 s[22:23], s[84:85], 20
	s_cmp_eq_u32 s52, 0
	v_mov_b64_e32 v[0:1], 0x3a0
	s_cselect_b32 s31, s14, s50
	v_cmp_lt_i64_e32 vcc, s[76:77], v[0:1]
	s_cselect_b32 s30, s15, s51
	s_cselect_b32 s38, s8, s14
	s_cselect_b32 s39, s9, s15
	s_add_u32 s76, s31, s22
	s_addc_u32 s77, s30, s23
	s_and_b64 s[22:23], vcc, exec
	s_cselect_b32 s30, s77, s89
	s_cselect_b32 s31, s76, s88
	s_ashr_i32 s83, s82, 31
	s_lshl_b64 s[22:23], s[82:83], 20
	s_add_u32 s86, s38, s22
	s_addc_u32 s87, s39, s23
	s_and_b64 s[22:23], vcc, exec
	s_cselect_b32 s38, s87, s91
	s_cselect_b32 s39, s86, s90
	s_add_u32 s88, s88, 0x80080
	s_addc_u32 s89, s89, 0
	s_add_u32 s41, s90, 0x100
	s_addc_u32 s42, s91, 0
	s_mov_b32 s43, -2
	s_add_u32 s22, s88, 0xfff80080
	s_addc_u32 s23, s89, -1
	s_add_u32 s44, s88, 0xfff80000
	s_addc_u32 s45, s89, -1
	s_cmp_eq_u32 s43, 28
	s_cselect_b32 s23, s30, s23
	s_cselect_b32 s22, s31, s22
	s_cselect_b32 s91, s38, s42
	s_cselect_b32 s90, s39, s41
	ds_read_b128 v[144:147], v222
	ds_read_b128 v[148:151], v222 offset:1024
	ds_read_b128 v[152:155], v222 offset:2048
	ds_read_b128 v[156:159], v222 offset:3072
	ds_read_b128 v[160:163], v223
	ds_read_b128 v[164:167], v223 offset:1024
	ds_read_b128 v[168:171], v223 offset:2048
	ds_read_b128 v[172:175], v223 offset:3072
	s_mov_b32 m0, s92
	ds_read_b128 v[176:179], v143
	ds_read_b128 v[180:183], v143 offset:1024
	ds_read_b128 v[184:187], v143 offset:2048
	ds_read_b128 v[188:191], v143 offset:3072
	ds_read_b128 v[192:195], v143 offset:4096
	ds_read_b128 v[196:199], v143 offset:5120
	ds_read_b128 v[200:203], v143 offset:6144
	ds_read_b128 v[204:207], v143 offset:7168
	global_load_lds_dwordx4 v128, s[44:45]
	s_mov_b32 m0, s6
	s_nop 0
	global_load_lds_dwordx4 v132, s[44:45]
	s_add_i32 m0, s57, 0xc000
	s_nop 0
	global_load_lds_dwordx4 v136, s[88:89]
	s_add_i32 m0, s57, 0xe000
	s_nop 0
	global_load_lds_dwordx4 v138, s[88:89]
	s_waitcnt vmcnt(8)
	s_waitcnt lgkmcnt(0)
	s_barrier
	v_mfma_f32_16x16x32_bf16 v[124:127], v[144:147], v[176:179], 0
	v_mfma_f32_16x16x32_bf16 v[120:123], v[152:155], v[176:179], 0
	v_mfma_f32_16x16x32_bf16 v[116:119], v[144:147], v[184:187], 0
	v_mfma_f32_16x16x32_bf16 v[112:115], v[152:155], v[184:187], 0
	v_mfma_f32_16x16x32_bf16 v[100:103], v[144:147], v[192:195], 0
	v_mfma_f32_16x16x32_bf16 v[96:99], v[152:155], v[192:195], 0
	v_mfma_f32_16x16x32_bf16 v[84:87], v[144:147], v[200:203], 0
	v_mfma_f32_16x16x32_bf16 v[80:83], v[152:155], v[200:203], 0
	v_mfma_f32_16x16x32_bf16 v[124:127], v[148:151], v[180:183], v[124:127]
	v_mfma_f32_16x16x32_bf16 v[120:123], v[156:159], v[180:183], v[120:123]
	v_mfma_f32_16x16x32_bf16 v[116:119], v[148:151], v[188:191], v[116:119]
	v_mfma_f32_16x16x32_bf16 v[112:115], v[156:159], v[188:191], v[112:115]
	v_mfma_f32_16x16x32_bf16 v[100:103], v[148:151], v[196:199], v[100:103]
	v_mfma_f32_16x16x32_bf16 v[96:99], v[156:159], v[196:199], v[96:99]
	v_mfma_f32_16x16x32_bf16 v[84:87], v[148:151], v[204:207], v[84:87]
	v_mfma_f32_16x16x32_bf16 v[80:83], v[156:159], v[204:207], v[80:83]
	v_mfma_f32_16x16x32_bf16 v[108:111], v[160:163], v[176:179], 0
	v_mfma_f32_16x16x32_bf16 v[104:107], v[168:171], v[176:179], 0
	v_mfma_f32_16x16x32_bf16 v[92:95], v[160:163], v[184:187], 0
	v_mfma_f32_16x16x32_bf16 v[88:91], v[168:171], v[184:187], 0
	v_mfma_f32_16x16x32_bf16 v[76:79], v[160:163], v[192:195], 0
	v_mfma_f32_16x16x32_bf16 v[72:75], v[168:171], v[192:195], 0
	v_mfma_f32_16x16x32_bf16 v[68:71], v[160:163], v[200:203], 0
	v_mfma_f32_16x16x32_bf16 v[64:67], v[168:171], v[200:203], 0
	v_mfma_f32_16x16x32_bf16 v[108:111], v[164:167], v[180:183], v[108:111]
	v_mfma_f32_16x16x32_bf16 v[104:107], v[172:175], v[180:183], v[104:107]
	v_mfma_f32_16x16x32_bf16 v[92:95], v[164:167], v[188:191], v[92:95]
	v_mfma_f32_16x16x32_bf16 v[88:91], v[172:175], v[188:191], v[88:91]
	v_mfma_f32_16x16x32_bf16 v[76:79], v[164:167], v[196:199], v[76:79]
	v_mfma_f32_16x16x32_bf16 v[72:75], v[172:175], v[196:199], v[72:75]
	v_mfma_f32_16x16x32_bf16 v[68:71], v[164:167], v[204:207], v[68:71]
	v_mfma_f32_16x16x32_bf16 v[64:67], v[172:175], v[204:207], v[64:67]
	s_barrier
	s_add_i32 m0, s96, 0x10000
	ds_read_b128 v[176:179], v143 offset:16384
	ds_read_b128 v[180:183], v143 offset:17408
	ds_read_b128 v[184:187], v143 offset:18432
	ds_read_b128 v[188:191], v143 offset:19456
	ds_read_b128 v[192:195], v143 offset:20480
	ds_read_b128 v[196:199], v143 offset:21504
	ds_read_b128 v[200:203], v143 offset:22528
	ds_read_b128 v[204:207], v143 offset:23552
	global_load_lds_dwordx4 v130, s[90:91]
	s_add_i32 m0, s96, 0x12000
	s_add_u32 s44, s90, 0x80000
	s_addc_u32 s45, s91, 0
	global_load_lds_dwordx4 v134, s[90:91]
	s_add_i32 m0, s96, 0x14000
	s_nop 0
	global_load_lds_dwordx4 v130, s[44:45]
	s_add_i32 m0, s96, 0x16000
	s_nop 0
	global_load_lds_dwordx4 v134, s[44:45]
	s_waitcnt vmcnt(6)
	s_waitcnt lgkmcnt(0)
	s_barrier
	v_mfma_f32_16x16x32_bf16 v[60:63], v[144:147], v[176:179], 0
	v_mfma_f32_16x16x32_bf16 v[56:59], v[152:155], v[176:179], 0
	v_mfma_f32_16x16x32_bf16 v[52:55], v[144:147], v[184:187], 0
	v_mfma_f32_16x16x32_bf16 v[48:51], v[152:155], v[184:187], 0
	v_mfma_f32_16x16x32_bf16 v[36:39], v[144:147], v[192:195], 0
	v_mfma_f32_16x16x32_bf16 v[32:35], v[152:155], v[192:195], 0
	v_mfma_f32_16x16x32_bf16 v[20:23], v[144:147], v[200:203], 0
	v_mfma_f32_16x16x32_bf16 v[16:19], v[152:155], v[200:203], 0
	v_mfma_f32_16x16x32_bf16 v[60:63], v[148:151], v[180:183], v[60:63]
	v_mfma_f32_16x16x32_bf16 v[56:59], v[156:159], v[180:183], v[56:59]
	v_mfma_f32_16x16x32_bf16 v[52:55], v[148:151], v[188:191], v[52:55]
	v_mfma_f32_16x16x32_bf16 v[48:51], v[156:159], v[188:191], v[48:51]
	v_mfma_f32_16x16x32_bf16 v[36:39], v[148:151], v[196:199], v[36:39]
	v_mfma_f32_16x16x32_bf16 v[32:35], v[156:159], v[196:199], v[32:35]
	v_mfma_f32_16x16x32_bf16 v[20:23], v[148:151], v[204:207], v[20:23]
	v_mfma_f32_16x16x32_bf16 v[16:19], v[156:159], v[204:207], v[16:19]
	v_mfma_f32_16x16x32_bf16 v[44:47], v[160:163], v[176:179], 0
	v_mfma_f32_16x16x32_bf16 v[40:43], v[168:171], v[176:179], 0
	v_mfma_f32_16x16x32_bf16 v[28:31], v[160:163], v[184:187], 0
	v_mfma_f32_16x16x32_bf16 v[24:27], v[168:171], v[184:187], 0
	v_mfma_f32_16x16x32_bf16 v[12:15], v[160:163], v[192:195], 0
	v_mfma_f32_16x16x32_bf16 v[8:11], v[168:171], v[192:195], 0
	v_mfma_f32_16x16x32_bf16 v[4:7], v[160:163], v[200:203], 0
	v_mfma_f32_16x16x32_bf16 v[0:3], v[168:171], v[200:203], 0
	v_mfma_f32_16x16x32_bf16 v[44:47], v[164:167], v[180:183], v[44:47]
	v_mfma_f32_16x16x32_bf16 v[40:43], v[172:175], v[180:183], v[40:43]
	v_mfma_f32_16x16x32_bf16 v[28:31], v[164:167], v[188:191], v[28:31]
	v_mfma_f32_16x16x32_bf16 v[24:27], v[172:175], v[188:191], v[24:27]
	v_mfma_f32_16x16x32_bf16 v[12:15], v[164:167], v[196:199], v[12:15]
	v_mfma_f32_16x16x32_bf16 v[8:11], v[172:175], v[196:199], v[8:11]
	v_mfma_f32_16x16x32_bf16 v[4:7], v[164:167], v[204:207], v[4:7]
	v_mfma_f32_16x16x32_bf16 v[0:3], v[172:175], v[204:207], v[0:3]
	s_barrier
	ds_read_b128 v[144:147], v224
	ds_read_b128 v[148:151], v224 offset:1024
	ds_read_b128 v[152:155], v224 offset:2048
	ds_read_b128 v[156:159], v224 offset:3072
	ds_read_b128 v[160:163], v225
	ds_read_b128 v[164:167], v225 offset:1024
	ds_read_b128 v[168:171], v225 offset:2048
	ds_read_b128 v[172:175], v225 offset:3072
	ds_read_b128 v[176:179], v143 offset:32768
	ds_read_b128 v[180:183], v143 offset:33792
	ds_read_b128 v[184:187], v143 offset:34816
	ds_read_b128 v[188:191], v143 offset:35840
	ds_read_b128 v[192:195], v143 offset:36864
	ds_read_b128 v[196:199], v143 offset:37888
	ds_read_b128 v[200:203], v143 offset:38912
	ds_read_b128 v[204:207], v143 offset:39936
	s_mov_b32 m0, s57
	s_nop 0
	global_load_lds_dwordx4 v128, s[22:23]
	s_mov_b32 m0, s97
	s_nop 0
	global_load_lds_dwordx4 v132, s[22:23]
	s_mov_b32 m0, s93
	s_add_u32 s22, s22, 0x80000
	s_addc_u32 s23, s23, 0
	global_load_lds_dwordx4 v128, s[22:23]
	s_mov_b32 m0, s94
	s_nop 0
	global_load_lds_dwordx4 v132, s[22:23]
	s_waitcnt vmcnt(8)
	s_waitcnt lgkmcnt(0)
	s_barrier
	v_mfma_f32_16x16x32_bf16 v[124:127], v[144:147], v[176:179], v[124:127]
	v_mfma_f32_16x16x32_bf16 v[120:123], v[152:155], v[176:179], v[120:123]
	v_mfma_f32_16x16x32_bf16 v[116:119], v[144:147], v[184:187], v[116:119]
	v_mfma_f32_16x16x32_bf16 v[112:115], v[152:155], v[184:187], v[112:115]
	v_mfma_f32_16x16x32_bf16 v[100:103], v[144:147], v[192:195], v[100:103]
	v_mfma_f32_16x16x32_bf16 v[96:99], v[152:155], v[192:195], v[96:99]
	v_mfma_f32_16x16x32_bf16 v[84:87], v[144:147], v[200:203], v[84:87]
	v_mfma_f32_16x16x32_bf16 v[80:83], v[152:155], v[200:203], v[80:83]
	v_mfma_f32_16x16x32_bf16 v[124:127], v[148:151], v[180:183], v[124:127]
	v_mfma_f32_16x16x32_bf16 v[120:123], v[156:159], v[180:183], v[120:123]
	v_mfma_f32_16x16x32_bf16 v[116:119], v[148:151], v[188:191], v[116:119]
	v_mfma_f32_16x16x32_bf16 v[112:115], v[156:159], v[188:191], v[112:115]
	v_mfma_f32_16x16x32_bf16 v[100:103], v[148:151], v[196:199], v[100:103]
	v_mfma_f32_16x16x32_bf16 v[96:99], v[156:159], v[196:199], v[96:99]
	v_mfma_f32_16x16x32_bf16 v[84:87], v[148:151], v[204:207], v[84:87]
	v_mfma_f32_16x16x32_bf16 v[80:83], v[156:159], v[204:207], v[80:83]
	v_mfma_f32_16x16x32_bf16 v[108:111], v[160:163], v[176:179], v[108:111]
	v_mfma_f32_16x16x32_bf16 v[104:107], v[168:171], v[176:179], v[104:107]
	v_mfma_f32_16x16x32_bf16 v[92:95], v[160:163], v[184:187], v[92:95]
	v_mfma_f32_16x16x32_bf16 v[88:91], v[168:171], v[184:187], v[88:91]
	v_mfma_f32_16x16x32_bf16 v[76:79], v[160:163], v[192:195], v[76:79]
	v_mfma_f32_16x16x32_bf16 v[72:75], v[168:171], v[192:195], v[72:75]
	v_mfma_f32_16x16x32_bf16 v[68:71], v[160:163], v[200:203], v[68:71]
	v_mfma_f32_16x16x32_bf16 v[64:67], v[168:171], v[200:203], v[64:67]
	v_mfma_f32_16x16x32_bf16 v[108:111], v[164:167], v[180:183], v[108:111]
	v_mfma_f32_16x16x32_bf16 v[104:107], v[172:175], v[180:183], v[104:107]
	v_mfma_f32_16x16x32_bf16 v[92:95], v[164:167], v[188:191], v[92:95]
	v_mfma_f32_16x16x32_bf16 v[88:91], v[172:175], v[188:191], v[88:91]
	v_mfma_f32_16x16x32_bf16 v[76:79], v[164:167], v[196:199], v[76:79]
	v_mfma_f32_16x16x32_bf16 v[72:75], v[172:175], v[196:199], v[72:75]
	v_mfma_f32_16x16x32_bf16 v[68:71], v[164:167], v[204:207], v[68:71]
	v_mfma_f32_16x16x32_bf16 v[64:67], v[172:175], v[204:207], v[64:67]
	s_barrier
	s_add_i32 m0, s96, 0x17f80
	ds_read_b128 v[176:179], v143 offset:49152
	ds_read_b128 v[180:183], v143 offset:50176
	ds_read_b128 v[184:187], v143 offset:51200
	ds_read_b128 v[188:191], v143 offset:52224
	ds_read_b128 v[192:195], v143 offset:53248
	ds_read_b128 v[196:199], v143 offset:54272
	ds_read_b128 v[200:203], v143 offset:55296
	ds_read_b128 v[204:207], v143 offset:56320
	global_load_lds_dwordx4 v130, s[90:91] offset:128
	s_add_i32 m0, s96, 0x19f80
	s_add_u32 s22, s90, 0x80080
	s_addc_u32 s23, s91, 0
	global_load_lds_dwordx4 v134, s[90:91] offset:128
	s_add_i32 m0, s96, 0x1c000
	s_nop 0
	global_load_lds_dwordx4 v130, s[22:23]
	s_add_i32 m0, s96, 0x1e000
	s_nop 0
	global_load_lds_dwordx4 v134, s[22:23]
	s_waitcnt vmcnt(6)
	s_waitcnt lgkmcnt(0)
	s_barrier
	v_mfma_f32_16x16x32_bf16 v[60:63], v[144:147], v[176:179], v[60:63]
	v_mfma_f32_16x16x32_bf16 v[56:59], v[152:155], v[176:179], v[56:59]
	s_add_i32 s43, s43, 2
	v_mfma_f32_16x16x32_bf16 v[52:55], v[144:147], v[184:187], v[52:55]
	s_add_u32 s88, s88, 0x100
	s_addc_u32 s89, s89, 0
	v_mfma_f32_16x16x32_bf16 v[48:51], v[152:155], v[184:187], v[48:51]
	s_add_u32 s41, s41, 0x100
	s_addc_u32 s42, s42, 0
	v_mfma_f32_16x16x32_bf16 v[36:39], v[144:147], v[192:195], v[36:39]
	s_add_u32 s22, s88, 0xfff80080
	s_addc_u32 s23, s89, -1
	v_mfma_f32_16x16x32_bf16 v[32:35], v[152:155], v[192:195], v[32:35]
	s_add_u32 s44, s88, 0xfff80000
	s_addc_u32 s45, s89, -1
	v_mfma_f32_16x16x32_bf16 v[20:23], v[144:147], v[200:203], v[20:23]
	s_cmp_eq_u32 s43, 28
	s_cselect_b32 s23, s30, s23
	s_cselect_b32 s22, s31, s22
	s_cselect_b32 s91, s38, s42
	s_cselect_b32 s90, s39, s41
	v_mfma_f32_16x16x32_bf16 v[16:19], v[152:155], v[200:203], v[16:19]
	s_cmp_gt_u32 s43, 29
	v_mfma_f32_16x16x32_bf16 v[60:63], v[148:151], v[180:183], v[60:63]
	v_mfma_f32_16x16x32_bf16 v[56:59], v[156:159], v[180:183], v[56:59]
	v_mfma_f32_16x16x32_bf16 v[52:55], v[148:151], v[188:191], v[52:55]
	v_mfma_f32_16x16x32_bf16 v[48:51], v[156:159], v[188:191], v[48:51]
	v_mfma_f32_16x16x32_bf16 v[36:39], v[148:151], v[196:199], v[36:39]
	v_mfma_f32_16x16x32_bf16 v[32:35], v[156:159], v[196:199], v[32:35]
	v_mfma_f32_16x16x32_bf16 v[20:23], v[148:151], v[204:207], v[20:23]
	v_mfma_f32_16x16x32_bf16 v[16:19], v[156:159], v[204:207], v[16:19]
	v_mfma_f32_16x16x32_bf16 v[44:47], v[160:163], v[176:179], v[44:47]
	v_mfma_f32_16x16x32_bf16 v[40:43], v[168:171], v[176:179], v[40:43]
	v_mfma_f32_16x16x32_bf16 v[28:31], v[160:163], v[184:187], v[28:31]
	v_mfma_f32_16x16x32_bf16 v[24:27], v[168:171], v[184:187], v[24:27]
	v_mfma_f32_16x16x32_bf16 v[12:15], v[160:163], v[192:195], v[12:15]
	v_mfma_f32_16x16x32_bf16 v[8:11], v[168:171], v[192:195], v[8:11]
	v_mfma_f32_16x16x32_bf16 v[4:7], v[160:163], v[200:203], v[4:7]
	v_mfma_f32_16x16x32_bf16 v[0:3], v[168:171], v[200:203], v[0:3]
	v_mfma_f32_16x16x32_bf16 v[44:47], v[164:167], v[180:183], v[44:47]
	v_mfma_f32_16x16x32_bf16 v[40:43], v[172:175], v[180:183], v[40:43]
	v_mfma_f32_16x16x32_bf16 v[28:31], v[164:167], v[188:191], v[28:31]
	v_mfma_f32_16x16x32_bf16 v[24:27], v[172:175], v[188:191], v[24:27]
	v_mfma_f32_16x16x32_bf16 v[12:15], v[164:167], v[196:199], v[12:15]
	v_mfma_f32_16x16x32_bf16 v[8:11], v[172:175], v[196:199], v[8:11]
	v_mfma_f32_16x16x32_bf16 v[4:7], v[164:167], v[204:207], v[4:7]
	v_mfma_f32_16x16x32_bf16 v[0:3], v[172:175], v[204:207], v[0:3]
	s_barrier
	s_cbranch_scc0 .LBB0_631
.LBB0_631:
	ds_read_b128 v[144:147], v222
	ds_read_b128 v[148:151], v222 offset:1024
	ds_read_b128 v[152:155], v222 offset:2048
	ds_read_b128 v[156:159], v222 offset:3072
	ds_read_b128 v[160:163], v223
	ds_read_b128 v[164:167], v223 offset:1024
	ds_read_b128 v[168:171], v223 offset:2048
	ds_read_b128 v[172:175], v223 offset:3072
	s_mov_b32 m0, s92
	ds_read_b128 v[176:179], v143
	ds_read_b128 v[180:183], v143 offset:1024
	ds_read_b128 v[184:187], v143 offset:2048
	ds_read_b128 v[188:191], v143 offset:3072
	ds_read_b128 v[192:195], v143 offset:4096
	ds_read_b128 v[196:199], v143 offset:5120
	ds_read_b128 v[200:203], v143 offset:6144
	ds_read_b128 v[204:207], v143 offset:7168
	global_load_lds_dwordx4 v128, s[44:45]
	s_mov_b32 m0, s6
	s_nop 0
	global_load_lds_dwordx4 v132, s[44:45]
	s_add_i32 m0, s57, 0xc000
	s_nop 0
	global_load_lds_dwordx4 v136, s[88:89]
	s_add_i32 m0, s57, 0xe000
	s_nop 0
	global_load_lds_dwordx4 v138, s[88:89]
	s_waitcnt vmcnt(8)
	s_waitcnt lgkmcnt(0)
	s_barrier
	v_mfma_f32_16x16x32_bf16 v[124:127], v[144:147], v[176:179], v[124:127]
	v_mfma_f32_16x16x32_bf16 v[120:123], v[152:155], v[176:179], v[120:123]
	v_mfma_f32_16x16x32_bf16 v[116:119], v[144:147], v[184:187], v[116:119]
	v_mfma_f32_16x16x32_bf16 v[112:115], v[152:155], v[184:187], v[112:115]
	v_mfma_f32_16x16x32_bf16 v[100:103], v[144:147], v[192:195], v[100:103]
	v_mfma_f32_16x16x32_bf16 v[96:99], v[152:155], v[192:195], v[96:99]
	v_mfma_f32_16x16x32_bf16 v[84:87], v[144:147], v[200:203], v[84:87]
	v_mfma_f32_16x16x32_bf16 v[80:83], v[152:155], v[200:203], v[80:83]
	v_mfma_f32_16x16x32_bf16 v[124:127], v[148:151], v[180:183], v[124:127]
	v_mfma_f32_16x16x32_bf16 v[120:123], v[156:159], v[180:183], v[120:123]
	v_mfma_f32_16x16x32_bf16 v[116:119], v[148:151], v[188:191], v[116:119]
	v_mfma_f32_16x16x32_bf16 v[112:115], v[156:159], v[188:191], v[112:115]
	v_mfma_f32_16x16x32_bf16 v[100:103], v[148:151], v[196:199], v[100:103]
	v_mfma_f32_16x16x32_bf16 v[96:99], v[156:159], v[196:199], v[96:99]
	v_mfma_f32_16x16x32_bf16 v[84:87], v[148:151], v[204:207], v[84:87]
	v_mfma_f32_16x16x32_bf16 v[80:83], v[156:159], v[204:207], v[80:83]
	v_mfma_f32_16x16x32_bf16 v[108:111], v[160:163], v[176:179], v[108:111]
	v_mfma_f32_16x16x32_bf16 v[104:107], v[168:171], v[176:179], v[104:107]
	v_mfma_f32_16x16x32_bf16 v[92:95], v[160:163], v[184:187], v[92:95]
	v_mfma_f32_16x16x32_bf16 v[88:91], v[168:171], v[184:187], v[88:91]
	v_mfma_f32_16x16x32_bf16 v[76:79], v[160:163], v[192:195], v[76:79]
	v_mfma_f32_16x16x32_bf16 v[72:75], v[168:171], v[192:195], v[72:75]
	v_mfma_f32_16x16x32_bf16 v[68:71], v[160:163], v[200:203], v[68:71]
	v_mfma_f32_16x16x32_bf16 v[64:67], v[168:171], v[200:203], v[64:67]
	v_mfma_f32_16x16x32_bf16 v[108:111], v[164:167], v[180:183], v[108:111]
	v_mfma_f32_16x16x32_bf16 v[104:107], v[172:175], v[180:183], v[104:107]
	v_mfma_f32_16x16x32_bf16 v[92:95], v[164:167], v[188:191], v[92:95]
	v_mfma_f32_16x16x32_bf16 v[88:91], v[172:175], v[188:191], v[88:91]
	v_mfma_f32_16x16x32_bf16 v[76:79], v[164:167], v[196:199], v[76:79]
	v_mfma_f32_16x16x32_bf16 v[72:75], v[172:175], v[196:199], v[72:75]
	v_mfma_f32_16x16x32_bf16 v[68:71], v[164:167], v[204:207], v[68:71]
	v_mfma_f32_16x16x32_bf16 v[64:67], v[172:175], v[204:207], v[64:67]
	s_barrier
	s_add_i32 m0, s96, 0x10000
	ds_read_b128 v[176:179], v143 offset:16384
	ds_read_b128 v[180:183], v143 offset:17408
	ds_read_b128 v[184:187], v143 offset:18432
	ds_read_b128 v[188:191], v143 offset:19456
	ds_read_b128 v[192:195], v143 offset:20480
	ds_read_b128 v[196:199], v143 offset:21504
	ds_read_b128 v[200:203], v143 offset:22528
	ds_read_b128 v[204:207], v143 offset:23552
	global_load_lds_dwordx4 v130, s[90:91]
	s_add_i32 m0, s96, 0x12000
	s_add_u32 s44, s90, 0x80000
	s_addc_u32 s45, s91, 0
	global_load_lds_dwordx4 v134, s[90:91]
	s_add_i32 m0, s96, 0x14000
	s_nop 0
	global_load_lds_dwordx4 v130, s[44:45]
	s_add_i32 m0, s96, 0x16000
	s_nop 0
	global_load_lds_dwordx4 v134, s[44:45]
	s_waitcnt vmcnt(6)
	s_waitcnt lgkmcnt(0)
	s_barrier
	v_mfma_f32_16x16x32_bf16 v[60:63], v[144:147], v[176:179], v[60:63]
	v_mfma_f32_16x16x32_bf16 v[56:59], v[152:155], v[176:179], v[56:59]
	v_mfma_f32_16x16x32_bf16 v[52:55], v[144:147], v[184:187], v[52:55]
	v_mfma_f32_16x16x32_bf16 v[48:51], v[152:155], v[184:187], v[48:51]
	v_mfma_f32_16x16x32_bf16 v[36:39], v[144:147], v[192:195], v[36:39]
	v_mfma_f32_16x16x32_bf16 v[32:35], v[152:155], v[192:195], v[32:35]
	v_mfma_f32_16x16x32_bf16 v[20:23], v[144:147], v[200:203], v[20:23]
	v_mfma_f32_16x16x32_bf16 v[16:19], v[152:155], v[200:203], v[16:19]
	v_mfma_f32_16x16x32_bf16 v[60:63], v[148:151], v[180:183], v[60:63]
	v_mfma_f32_16x16x32_bf16 v[56:59], v[156:159], v[180:183], v[56:59]
	v_mfma_f32_16x16x32_bf16 v[52:55], v[148:151], v[188:191], v[52:55]
	v_mfma_f32_16x16x32_bf16 v[48:51], v[156:159], v[188:191], v[48:51]
	v_mfma_f32_16x16x32_bf16 v[36:39], v[148:151], v[196:199], v[36:39]
	v_mfma_f32_16x16x32_bf16 v[32:35], v[156:159], v[196:199], v[32:35]
	v_mfma_f32_16x16x32_bf16 v[20:23], v[148:151], v[204:207], v[20:23]
	v_mfma_f32_16x16x32_bf16 v[16:19], v[156:159], v[204:207], v[16:19]
	v_mfma_f32_16x16x32_bf16 v[44:47], v[160:163], v[176:179], v[44:47]
	v_mfma_f32_16x16x32_bf16 v[40:43], v[168:171], v[176:179], v[40:43]
	v_mfma_f32_16x16x32_bf16 v[28:31], v[160:163], v[184:187], v[28:31]
	v_mfma_f32_16x16x32_bf16 v[24:27], v[168:171], v[184:187], v[24:27]
	v_mfma_f32_16x16x32_bf16 v[12:15], v[160:163], v[192:195], v[12:15]
	v_mfma_f32_16x16x32_bf16 v[8:11], v[168:171], v[192:195], v[8:11]
	v_mfma_f32_16x16x32_bf16 v[4:7], v[160:163], v[200:203], v[4:7]
	v_mfma_f32_16x16x32_bf16 v[0:3], v[168:171], v[200:203], v[0:3]
	v_mfma_f32_16x16x32_bf16 v[44:47], v[164:167], v[180:183], v[44:47]
	v_mfma_f32_16x16x32_bf16 v[40:43], v[172:175], v[180:183], v[40:43]
	v_mfma_f32_16x16x32_bf16 v[28:31], v[164:167], v[188:191], v[28:31]
	v_mfma_f32_16x16x32_bf16 v[24:27], v[172:175], v[188:191], v[24:27]
	v_mfma_f32_16x16x32_bf16 v[12:15], v[164:167], v[196:199], v[12:15]
	v_mfma_f32_16x16x32_bf16 v[8:11], v[172:175], v[196:199], v[8:11]
	v_mfma_f32_16x16x32_bf16 v[4:7], v[164:167], v[204:207], v[4:7]
	v_mfma_f32_16x16x32_bf16 v[0:3], v[172:175], v[204:207], v[0:3]
	s_barrier
	ds_read_b128 v[144:147], v224
	ds_read_b128 v[148:151], v224 offset:1024
	ds_read_b128 v[152:155], v224 offset:2048
	ds_read_b128 v[156:159], v224 offset:3072
	ds_read_b128 v[160:163], v225
	ds_read_b128 v[164:167], v225 offset:1024
	ds_read_b128 v[168:171], v225 offset:2048
	ds_read_b128 v[172:175], v225 offset:3072
	ds_read_b128 v[176:179], v143 offset:32768
	ds_read_b128 v[180:183], v143 offset:33792
	ds_read_b128 v[184:187], v143 offset:34816
	ds_read_b128 v[188:191], v143 offset:35840
	ds_read_b128 v[192:195], v143 offset:36864
	ds_read_b128 v[196:199], v143 offset:37888
	ds_read_b128 v[200:203], v143 offset:38912
	ds_read_b128 v[204:207], v143 offset:39936
	s_mov_b32 m0, s57
	s_nop 0
	global_load_lds_dwordx4 v128, s[22:23]
	s_mov_b32 m0, s97
	s_nop 0
	global_load_lds_dwordx4 v132, s[22:23]
	s_mov_b32 m0, s93
	s_add_u32 s22, s22, 0x80000
	s_addc_u32 s23, s23, 0
	global_load_lds_dwordx4 v128, s[22:23]
	s_mov_b32 m0, s94
	s_nop 0
	global_load_lds_dwordx4 v132, s[22:23]
	s_waitcnt vmcnt(8)
	s_waitcnt lgkmcnt(0)
	s_barrier
	v_mfma_f32_16x16x32_bf16 v[124:127], v[144:147], v[176:179], v[124:127]
	v_mfma_f32_16x16x32_bf16 v[120:123], v[152:155], v[176:179], v[120:123]
	v_mfma_f32_16x16x32_bf16 v[116:119], v[144:147], v[184:187], v[116:119]
	v_mfma_f32_16x16x32_bf16 v[112:115], v[152:155], v[184:187], v[112:115]
	v_mfma_f32_16x16x32_bf16 v[100:103], v[144:147], v[192:195], v[100:103]
	v_mfma_f32_16x16x32_bf16 v[96:99], v[152:155], v[192:195], v[96:99]
	v_mfma_f32_16x16x32_bf16 v[84:87], v[144:147], v[200:203], v[84:87]
	v_mfma_f32_16x16x32_bf16 v[80:83], v[152:155], v[200:203], v[80:83]
	v_mfma_f32_16x16x32_bf16 v[124:127], v[148:151], v[180:183], v[124:127]
	v_mfma_f32_16x16x32_bf16 v[120:123], v[156:159], v[180:183], v[120:123]
	v_mfma_f32_16x16x32_bf16 v[116:119], v[148:151], v[188:191], v[116:119]
	v_mfma_f32_16x16x32_bf16 v[112:115], v[156:159], v[188:191], v[112:115]
	v_mfma_f32_16x16x32_bf16 v[100:103], v[148:151], v[196:199], v[100:103]
	v_mfma_f32_16x16x32_bf16 v[96:99], v[156:159], v[196:199], v[96:99]
	v_mfma_f32_16x16x32_bf16 v[84:87], v[148:151], v[204:207], v[84:87]
	v_mfma_f32_16x16x32_bf16 v[80:83], v[156:159], v[204:207], v[80:83]
	v_mfma_f32_16x16x32_bf16 v[108:111], v[160:163], v[176:179], v[108:111]
	v_mfma_f32_16x16x32_bf16 v[104:107], v[168:171], v[176:179], v[104:107]
	v_mfma_f32_16x16x32_bf16 v[92:95], v[160:163], v[184:187], v[92:95]
	v_mfma_f32_16x16x32_bf16 v[88:91], v[168:171], v[184:187], v[88:91]
	v_mfma_f32_16x16x32_bf16 v[76:79], v[160:163], v[192:195], v[76:79]
	v_mfma_f32_16x16x32_bf16 v[72:75], v[168:171], v[192:195], v[72:75]
	v_mfma_f32_16x16x32_bf16 v[68:71], v[160:163], v[200:203], v[68:71]
	v_mfma_f32_16x16x32_bf16 v[64:67], v[168:171], v[200:203], v[64:67]
	v_mfma_f32_16x16x32_bf16 v[108:111], v[164:167], v[180:183], v[108:111]
	v_mfma_f32_16x16x32_bf16 v[104:107], v[172:175], v[180:183], v[104:107]
	v_mfma_f32_16x16x32_bf16 v[92:95], v[164:167], v[188:191], v[92:95]
	v_mfma_f32_16x16x32_bf16 v[88:91], v[172:175], v[188:191], v[88:91]
	v_mfma_f32_16x16x32_bf16 v[76:79], v[164:167], v[196:199], v[76:79]
	v_mfma_f32_16x16x32_bf16 v[72:75], v[172:175], v[196:199], v[72:75]
	v_mfma_f32_16x16x32_bf16 v[68:71], v[164:167], v[204:207], v[68:71]
	v_mfma_f32_16x16x32_bf16 v[64:67], v[172:175], v[204:207], v[64:67]
	s_barrier
	s_add_i32 m0, s96, 0x17f80
	ds_read_b128 v[176:179], v143 offset:49152
	ds_read_b128 v[180:183], v143 offset:50176
	ds_read_b128 v[184:187], v143 offset:51200
	ds_read_b128 v[188:191], v143 offset:52224
	ds_read_b128 v[192:195], v143 offset:53248
	ds_read_b128 v[196:199], v143 offset:54272
	ds_read_b128 v[200:203], v143 offset:55296
	ds_read_b128 v[204:207], v143 offset:56320
	global_load_lds_dwordx4 v130, s[90:91] offset:128
	s_add_i32 m0, s96, 0x19f80
	s_add_u32 s22, s90, 0x80080
	s_addc_u32 s23, s91, 0
	global_load_lds_dwordx4 v134, s[90:91] offset:128
	s_add_i32 m0, s96, 0x1c000
	s_nop 0
	global_load_lds_dwordx4 v130, s[22:23]
	s_add_i32 m0, s96, 0x1e000
	s_nop 0
	global_load_lds_dwordx4 v134, s[22:23]
	s_waitcnt vmcnt(6)
	s_waitcnt lgkmcnt(0)
	s_barrier
	v_mfma_f32_16x16x32_bf16 v[60:63], v[144:147], v[176:179], v[60:63]
	v_mfma_f32_16x16x32_bf16 v[56:59], v[152:155], v[176:179], v[56:59]
	s_add_i32 s43, s43, 2
	v_mfma_f32_16x16x32_bf16 v[52:55], v[144:147], v[184:187], v[52:55]
	s_add_u32 s88, s88, 0x100
	s_addc_u32 s89, s89, 0
	v_mfma_f32_16x16x32_bf16 v[48:51], v[152:155], v[184:187], v[48:51]
	s_add_u32 s41, s41, 0x100
	s_addc_u32 s42, s42, 0
	v_mfma_f32_16x16x32_bf16 v[36:39], v[144:147], v[192:195], v[36:39]
	s_add_u32 s22, s88, 0xfff80080
	s_addc_u32 s23, s89, -1
	v_mfma_f32_16x16x32_bf16 v[32:35], v[152:155], v[192:195], v[32:35]
	s_add_u32 s44, s88, 0xfff80000
	s_addc_u32 s45, s89, -1
	v_mfma_f32_16x16x32_bf16 v[20:23], v[144:147], v[200:203], v[20:23]
	s_cmp_eq_u32 s43, 28
	s_cselect_b32 s23, s30, s23
	s_cselect_b32 s22, s31, s22
	s_cselect_b32 s91, s38, s42
	s_cselect_b32 s90, s39, s41
	v_mfma_f32_16x16x32_bf16 v[16:19], v[152:155], v[200:203], v[16:19]
	s_cmp_gt_u32 s43, 29
	v_mfma_f32_16x16x32_bf16 v[60:63], v[148:151], v[180:183], v[60:63]
	v_mfma_f32_16x16x32_bf16 v[56:59], v[156:159], v[180:183], v[56:59]
	v_mfma_f32_16x16x32_bf16 v[52:55], v[148:151], v[188:191], v[52:55]
	v_mfma_f32_16x16x32_bf16 v[48:51], v[156:159], v[188:191], v[48:51]
	v_mfma_f32_16x16x32_bf16 v[36:39], v[148:151], v[196:199], v[36:39]
	v_mfma_f32_16x16x32_bf16 v[32:35], v[156:159], v[196:199], v[32:35]
	v_mfma_f32_16x16x32_bf16 v[20:23], v[148:151], v[204:207], v[20:23]
	v_mfma_f32_16x16x32_bf16 v[16:19], v[156:159], v[204:207], v[16:19]
	v_mfma_f32_16x16x32_bf16 v[44:47], v[160:163], v[176:179], v[44:47]
	v_mfma_f32_16x16x32_bf16 v[40:43], v[168:171], v[176:179], v[40:43]
	v_mfma_f32_16x16x32_bf16 v[28:31], v[160:163], v[184:187], v[28:31]
	v_mfma_f32_16x16x32_bf16 v[24:27], v[168:171], v[184:187], v[24:27]
	v_mfma_f32_16x16x32_bf16 v[12:15], v[160:163], v[192:195], v[12:15]
	v_mfma_f32_16x16x32_bf16 v[8:11], v[168:171], v[192:195], v[8:11]
	v_mfma_f32_16x16x32_bf16 v[4:7], v[160:163], v[200:203], v[4:7]
	v_mfma_f32_16x16x32_bf16 v[0:3], v[168:171], v[200:203], v[0:3]
	v_mfma_f32_16x16x32_bf16 v[44:47], v[164:167], v[180:183], v[44:47]
	v_mfma_f32_16x16x32_bf16 v[40:43], v[172:175], v[180:183], v[40:43]
	v_mfma_f32_16x16x32_bf16 v[28:31], v[164:167], v[188:191], v[28:31]
	v_mfma_f32_16x16x32_bf16 v[24:27], v[172:175], v[188:191], v[24:27]
	v_mfma_f32_16x16x32_bf16 v[12:15], v[164:167], v[196:199], v[12:15]
	v_mfma_f32_16x16x32_bf16 v[8:11], v[172:175], v[196:199], v[8:11]
	v_mfma_f32_16x16x32_bf16 v[4:7], v[164:167], v[204:207], v[4:7]
	v_mfma_f32_16x16x32_bf16 v[0:3], v[172:175], v[204:207], v[0:3]
	s_barrier
	s_cbranch_scc0 .LBB0_631
	s_cmp_eq_u32 s40, 0
	s_cselect_b64 s[30:31], -1, 0
	s_cmp_lg_u32 s40, 0
	s_mov_b64 s[38:39], -1
	s_cbranch_scc0 .LBB0_634
	s_lshl_b32 s22, s80, 8
	s_or_b32 s22, s22, s53
	s_ashr_i32 s22, s22, 6
	s_mov_b64 s[38:39], 0

.LBB0_1259:
	ds_read_b128 v[142:145], v222
	ds_read_b128 v[146:149], v222 offset:1024
	ds_read_b128 v[150:153], v222 offset:2048
	ds_read_b128 v[154:157], v222 offset:3072
	ds_read_b128 v[158:161], v223
	ds_read_b128 v[162:165], v223 offset:1024
	ds_read_b128 v[166:169], v223 offset:2048
	ds_read_b128 v[170:173], v223 offset:3072
	s_mov_b32 m0, s9
	ds_read_b128 v[174:177], v140
	ds_read_b128 v[178:181], v140 offset:1024
	ds_read_b128 v[182:185], v140 offset:2048
	ds_read_b128 v[186:189], v140 offset:3072
	ds_read_b128 v[190:193], v140 offset:4096
	ds_read_b128 v[194:197], v140 offset:5120
	ds_read_b128 v[198:201], v140 offset:6144
	ds_read_b128 v[202:205], v140 offset:7168
	global_load_lds_dwordx4 v208, s[80:81]
	s_mov_b32 m0, s12
	s_nop 0
	global_load_lds_dwordx4 v128, s[80:81]
	s_add_i32 m0, s45, 0xc000
	s_nop 0
	global_load_lds_dwordx4 v136, s[92:93]
	s_add_i32 m0, s45, 0xe000
	s_nop 0
	global_load_lds_dwordx4 v134, s[92:93]
	s_waitcnt vmcnt(8)
	s_waitcnt lgkmcnt(0)
	s_barrier
	v_mfma_f32_16x16x32_bf16 v[124:127], v[142:145], v[174:177], v[124:127]
	v_mfma_f32_16x16x32_bf16 v[120:123], v[150:153], v[174:177], v[120:123]
	v_mfma_f32_16x16x32_bf16 v[108:111], v[142:145], v[182:185], v[108:111]
	v_mfma_f32_16x16x32_bf16 v[104:107], v[150:153], v[182:185], v[104:107]
	v_mfma_f32_16x16x32_bf16 v[92:95], v[142:145], v[190:193], v[92:95]
	v_mfma_f32_16x16x32_bf16 v[88:91], v[150:153], v[190:193], v[88:91]
	v_mfma_f32_16x16x32_bf16 v[76:79], v[142:145], v[198:201], v[76:79]
	v_mfma_f32_16x16x32_bf16 v[72:75], v[150:153], v[198:201], v[72:75]
	v_mfma_f32_16x16x32_bf16 v[124:127], v[146:149], v[178:181], v[124:127]
	v_mfma_f32_16x16x32_bf16 v[120:123], v[154:157], v[178:181], v[120:123]
	v_mfma_f32_16x16x32_bf16 v[108:111], v[146:149], v[186:189], v[108:111]
	v_mfma_f32_16x16x32_bf16 v[104:107], v[154:157], v[186:189], v[104:107]
	v_mfma_f32_16x16x32_bf16 v[92:95], v[146:149], v[194:197], v[92:95]
	v_mfma_f32_16x16x32_bf16 v[88:91], v[154:157], v[194:197], v[88:91]
	v_mfma_f32_16x16x32_bf16 v[76:79], v[146:149], v[202:205], v[76:79]
	v_mfma_f32_16x16x32_bf16 v[72:75], v[154:157], v[202:205], v[72:75]
	v_mfma_f32_16x16x32_bf16 v[116:119], v[158:161], v[174:177], v[116:119]
	v_mfma_f32_16x16x32_bf16 v[112:115], v[166:169], v[174:177], v[112:115]
	v_mfma_f32_16x16x32_bf16 v[100:103], v[158:161], v[182:185], v[100:103]
	v_mfma_f32_16x16x32_bf16 v[96:99], v[166:169], v[182:185], v[96:99]
	v_mfma_f32_16x16x32_bf16 v[84:87], v[158:161], v[190:193], v[84:87]
	v_mfma_f32_16x16x32_bf16 v[80:83], v[166:169], v[190:193], v[80:83]
	v_mfma_f32_16x16x32_bf16 v[68:71], v[158:161], v[198:201], v[68:71]
	v_mfma_f32_16x16x32_bf16 v[64:67], v[166:169], v[198:201], v[64:67]
	v_mfma_f32_16x16x32_bf16 v[116:119], v[162:165], v[178:181], v[116:119]
	v_mfma_f32_16x16x32_bf16 v[112:115], v[170:173], v[178:181], v[112:115]
	v_mfma_f32_16x16x32_bf16 v[100:103], v[162:165], v[186:189], v[100:103]
	v_mfma_f32_16x16x32_bf16 v[96:99], v[170:173], v[186:189], v[96:99]
	v_mfma_f32_16x16x32_bf16 v[84:87], v[162:165], v[194:197], v[84:87]
	v_mfma_f32_16x16x32_bf16 v[80:83], v[170:173], v[194:197], v[80:83]
	v_mfma_f32_16x16x32_bf16 v[68:71], v[162:165], v[202:205], v[68:71]
	v_mfma_f32_16x16x32_bf16 v[64:67], v[170:173], v[202:205], v[64:67]
	s_barrier
	s_add_i32 m0, s43, 0x10000
	ds_read_b128 v[174:177], v140 offset:16384
	ds_read_b128 v[178:181], v140 offset:17408
	ds_read_b128 v[182:185], v140 offset:18432
	ds_read_b128 v[186:189], v140 offset:19456
	ds_read_b128 v[190:193], v140 offset:20480
	ds_read_b128 v[194:197], v140 offset:21504
	ds_read_b128 v[198:201], v140 offset:22528
	ds_read_b128 v[202:205], v140 offset:23552
	global_load_lds_dwordx4 v208, vcc
	s_add_i32 m0, s43, 0x12000
	s_add_u32 s80, vcc_lo, 0x80000
	s_addc_u32 s81, vcc_hi, 0
	global_load_lds_dwordx4 v128, vcc
	s_add_i32 m0, s43, 0x14000
	s_nop 0
	global_load_lds_dwordx4 v208, s[80:81]
	s_add_i32 m0, s43, 0x16000
	s_nop 0
	global_load_lds_dwordx4 v128, s[80:81]
	s_waitcnt vmcnt(6)
	s_waitcnt lgkmcnt(0)
	s_barrier
	v_mfma_f32_16x16x32_bf16 v[60:63], v[142:145], v[174:177], v[60:63]
	v_mfma_f32_16x16x32_bf16 v[56:59], v[150:153], v[174:177], v[56:59]
	v_mfma_f32_16x16x32_bf16 v[44:47], v[142:145], v[182:185], v[44:47]
	v_mfma_f32_16x16x32_bf16 v[40:43], v[150:153], v[182:185], v[40:43]
	v_mfma_f32_16x16x32_bf16 v[28:31], v[142:145], v[190:193], v[28:31]
	v_mfma_f32_16x16x32_bf16 v[24:27], v[150:153], v[190:193], v[24:27]
	v_mfma_f32_16x16x32_bf16 v[12:15], v[142:145], v[198:201], v[12:15]
	v_mfma_f32_16x16x32_bf16 v[8:11], v[150:153], v[198:201], v[8:11]
	v_mfma_f32_16x16x32_bf16 v[60:63], v[146:149], v[178:181], v[60:63]
	v_mfma_f32_16x16x32_bf16 v[56:59], v[154:157], v[178:181], v[56:59]
	v_mfma_f32_16x16x32_bf16 v[44:47], v[146:149], v[186:189], v[44:47]
	v_mfma_f32_16x16x32_bf16 v[40:43], v[154:157], v[186:189], v[40:43]
	v_mfma_f32_16x16x32_bf16 v[28:31], v[146:149], v[194:197], v[28:31]
	v_mfma_f32_16x16x32_bf16 v[24:27], v[154:157], v[194:197], v[24:27]
	v_mfma_f32_16x16x32_bf16 v[12:15], v[146:149], v[202:205], v[12:15]
	v_mfma_f32_16x16x32_bf16 v[8:11], v[154:157], v[202:205], v[8:11]
	v_mfma_f32_16x16x32_bf16 v[52:55], v[158:161], v[174:177], v[52:55]
	v_mfma_f32_16x16x32_bf16 v[48:51], v[166:169], v[174:177], v[48:51]
	v_mfma_f32_16x16x32_bf16 v[36:39], v[158:161], v[182:185], v[36:39]
	v_mfma_f32_16x16x32_bf16 v[32:35], v[166:169], v[182:185], v[32:35]
	v_mfma_f32_16x16x32_bf16 v[20:23], v[158:161], v[190:193], v[20:23]
	v_mfma_f32_16x16x32_bf16 v[16:19], v[166:169], v[190:193], v[16:19]
	v_mfma_f32_16x16x32_bf16 v[4:7], v[158:161], v[198:201], v[4:7]
	v_mfma_f32_16x16x32_bf16 v[0:3], v[166:169], v[198:201], v[0:3]
	v_mfma_f32_16x16x32_bf16 v[52:55], v[162:165], v[178:181], v[52:55]
	v_mfma_f32_16x16x32_bf16 v[48:51], v[170:173], v[178:181], v[48:51]
	v_mfma_f32_16x16x32_bf16 v[36:39], v[162:165], v[186:189], v[36:39]
	v_mfma_f32_16x16x32_bf16 v[32:35], v[170:173], v[186:189], v[32:35]
	v_mfma_f32_16x16x32_bf16 v[20:23], v[162:165], v[194:197], v[20:23]
	v_mfma_f32_16x16x32_bf16 v[16:19], v[170:173], v[194:197], v[16:19]
	v_mfma_f32_16x16x32_bf16 v[4:7], v[162:165], v[202:205], v[4:7]
	v_mfma_f32_16x16x32_bf16 v[0:3], v[170:173], v[202:205], v[0:3]
	s_barrier
	ds_read_b128 v[142:145], v224
	ds_read_b128 v[146:149], v224 offset:1024
	ds_read_b128 v[150:153], v224 offset:2048
	ds_read_b128 v[154:157], v224 offset:3072
	ds_read_b128 v[158:161], v225
	ds_read_b128 v[162:165], v225 offset:1024
	ds_read_b128 v[166:169], v225 offset:2048
	ds_read_b128 v[170:173], v225 offset:3072
	ds_read_b128 v[174:177], v140 offset:32768
	ds_read_b128 v[178:181], v140 offset:33792
	ds_read_b128 v[182:185], v140 offset:34816
	ds_read_b128 v[186:189], v140 offset:35840
	ds_read_b128 v[190:193], v140 offset:36864
	ds_read_b128 v[194:197], v140 offset:37888
	ds_read_b128 v[198:201], v140 offset:38912
	ds_read_b128 v[202:205], v140 offset:39936
	s_mov_b32 m0, s45
	s_nop 0
	global_load_lds_dwordx4 v208, s[22:23]
	s_mov_b32 m0, s52
	s_nop 0
	global_load_lds_dwordx4 v128, s[22:23]
	s_mov_b32 m0, s53
	s_add_u32 s22, s22, 0x80000
	s_addc_u32 s23, s23, 0
	global_load_lds_dwordx4 v208, s[22:23]
	s_mov_b32 m0, s85
	s_nop 0
	global_load_lds_dwordx4 v128, s[22:23]
	s_waitcnt vmcnt(8)
	s_waitcnt lgkmcnt(0)
	s_barrier
	v_mfma_f32_16x16x32_bf16 v[124:127], v[142:145], v[174:177], v[124:127]
	v_mfma_f32_16x16x32_bf16 v[120:123], v[150:153], v[174:177], v[120:123]
	v_mfma_f32_16x16x32_bf16 v[108:111], v[142:145], v[182:185], v[108:111]
	v_mfma_f32_16x16x32_bf16 v[104:107], v[150:153], v[182:185], v[104:107]
	v_mfma_f32_16x16x32_bf16 v[92:95], v[142:145], v[190:193], v[92:95]
	v_mfma_f32_16x16x32_bf16 v[88:91], v[150:153], v[190:193], v[88:91]
	v_mfma_f32_16x16x32_bf16 v[76:79], v[142:145], v[198:201], v[76:79]
	v_mfma_f32_16x16x32_bf16 v[72:75], v[150:153], v[198:201], v[72:75]
	v_mfma_f32_16x16x32_bf16 v[124:127], v[146:149], v[178:181], v[124:127]
	v_mfma_f32_16x16x32_bf16 v[120:123], v[154:157], v[178:181], v[120:123]
	v_mfma_f32_16x16x32_bf16 v[108:111], v[146:149], v[186:189], v[108:111]
	v_mfma_f32_16x16x32_bf16 v[104:107], v[154:157], v[186:189], v[104:107]
	v_mfma_f32_16x16x32_bf16 v[92:95], v[146:149], v[194:197], v[92:95]
	v_mfma_f32_16x16x32_bf16 v[88:91], v[154:157], v[194:197], v[88:91]
	v_mfma_f32_16x16x32_bf16 v[76:79], v[146:149], v[202:205], v[76:79]
	v_mfma_f32_16x16x32_bf16 v[72:75], v[154:157], v[202:205], v[72:75]
	v_mfma_f32_16x16x32_bf16 v[116:119], v[158:161], v[174:177], v[116:119]
	v_mfma_f32_16x16x32_bf16 v[112:115], v[166:169], v[174:177], v[112:115]
	v_mfma_f32_16x16x32_bf16 v[100:103], v[158:161], v[182:185], v[100:103]
	v_mfma_f32_16x16x32_bf16 v[96:99], v[166:169], v[182:185], v[96:99]
	v_mfma_f32_16x16x32_bf16 v[84:87], v[158:161], v[190:193], v[84:87]
	v_mfma_f32_16x16x32_bf16 v[80:83], v[166:169], v[190:193], v[80:83]
	v_mfma_f32_16x16x32_bf16 v[68:71], v[158:161], v[198:201], v[68:71]
	v_mfma_f32_16x16x32_bf16 v[64:67], v[166:169], v[198:201], v[64:67]
	v_mfma_f32_16x16x32_bf16 v[116:119], v[162:165], v[178:181], v[116:119]
	v_mfma_f32_16x16x32_bf16 v[112:115], v[170:173], v[178:181], v[112:115]
	v_mfma_f32_16x16x32_bf16 v[100:103], v[162:165], v[186:189], v[100:103]
	v_mfma_f32_16x16x32_bf16 v[96:99], v[170:173], v[186:189], v[96:99]
	v_mfma_f32_16x16x32_bf16 v[84:87], v[162:165], v[194:197], v[84:87]
	v_mfma_f32_16x16x32_bf16 v[80:83], v[170:173], v[194:197], v[80:83]
	v_mfma_f32_16x16x32_bf16 v[68:71], v[162:165], v[202:205], v[68:71]
	v_mfma_f32_16x16x32_bf16 v[64:67], v[170:173], v[202:205], v[64:67]
	s_barrier
	s_add_i32 m0, s43, 0x17f80
	ds_read_b128 v[174:177], v140 offset:49152
	ds_read_b128 v[178:181], v140 offset:50176
	ds_read_b128 v[182:185], v140 offset:51200
	ds_read_b128 v[186:189], v140 offset:52224
	ds_read_b128 v[190:193], v140 offset:53248
	ds_read_b128 v[194:197], v140 offset:54272
	ds_read_b128 v[198:201], v140 offset:55296
	ds_read_b128 v[202:205], v140 offset:56320
	global_load_lds_dwordx4 v208, vcc offset:128
	s_add_i32 m0, s43, 0x19f80
	s_add_u32 s22, vcc_lo, 0x80080
	s_addc_u32 s23, vcc_hi, 0
	global_load_lds_dwordx4 v128, vcc offset:128
	s_add_i32 m0, s43, 0x1c000
	s_nop 0
	global_load_lds_dwordx4 v208, s[22:23]
	s_add_i32 m0, s43, 0x1e000
	s_nop 0
	global_load_lds_dwordx4 v128, s[22:23]
	s_waitcnt vmcnt(6)
	s_waitcnt lgkmcnt(0)
	s_barrier
	v_mfma_f32_16x16x32_bf16 v[60:63], v[142:145], v[174:177], v[60:63]
	v_mfma_f32_16x16x32_bf16 v[56:59], v[150:153], v[174:177], v[56:59]
	s_addk_i32 s44, 0x200
	v_mfma_f32_16x16x32_bf16 v[44:47], v[142:145], v[182:185], v[44:47]
	v_mfma_f32_16x16x32_bf16 v[40:43], v[150:153], v[182:185], v[40:43]
	s_add_u32 s76, s76, 0x100
	s_addc_u32 s77, s77, 0
	v_mfma_f32_16x16x32_bf16 v[28:31], v[142:145], v[190:193], v[28:31]
	v_mfma_f32_16x16x32_bf16 v[24:27], v[150:153], v[190:193], v[24:27]
	v_lshl_add_u64 v[136:137], v[136:137], 0, s[58:59]
	v_mfma_f32_16x16x32_bf16 v[12:15], v[142:145], v[198:201], v[12:15]
	v_mfma_f32_16x16x32_bf16 v[8:11], v[150:153], v[198:201], v[8:11]
	v_lshl_add_u64 v[134:135], v[134:135], 0, s[58:59]
	v_mfma_f32_16x16x32_bf16 v[60:63], v[146:149], v[178:181], v[60:63]
	v_mfma_f32_16x16x32_bf16 v[56:59], v[154:157], v[178:181], v[56:59]
	s_add_u32 s22, s92, s76
	s_addc_u32 s23, s93, s77
	v_mfma_f32_16x16x32_bf16 v[44:47], v[146:149], v[186:189], v[44:47]
	v_mfma_f32_16x16x32_bf16 v[40:43], v[154:157], v[186:189], v[40:43]
	s_add_u32 s80, s96, s76
	s_addc_u32 s81, s97, s77
	v_mfma_f32_16x16x32_bf16 v[28:31], v[146:149], v[194:197], v[28:31]
	v_mfma_f32_16x16x32_bf16 v[24:27], v[154:157], v[194:197], v[24:27]
	s_cmp_eq_u32 s44, 0
	s_cselect_b32 s23, s15, s23
	s_cselect_b32 s22, s91, s22
	s_cselect_b32 vcc_hi, s89, s81
	s_cselect_b32 vcc_lo, s8, s80
	v_mfma_f32_16x16x32_bf16 v[12:15], v[146:149], v[202:205], v[12:15]
	v_mfma_f32_16x16x32_bf16 v[8:11], v[154:157], v[202:205], v[8:11]
	s_add_u32 s80, s92, s76
	s_addc_u32 s81, s93, s77
	s_sub_u32 s80, s80, 0x80
	s_subb_u32 s81, s81, 0
	v_mfma_f32_16x16x32_bf16 v[52:55], v[158:161], v[174:177], v[52:55]
	s_cmp_gt_u32 s82, 29
	v_mfma_f32_16x16x32_bf16 v[48:51], v[166:169], v[174:177], v[48:51]
	v_mfma_f32_16x16x32_bf16 v[36:39], v[158:161], v[182:185], v[36:39]
	v_mfma_f32_16x16x32_bf16 v[32:35], v[166:169], v[182:185], v[32:35]
	v_mfma_f32_16x16x32_bf16 v[20:23], v[158:161], v[190:193], v[20:23]
	v_mfma_f32_16x16x32_bf16 v[16:19], v[166:169], v[190:193], v[16:19]
	v_mfma_f32_16x16x32_bf16 v[4:7], v[158:161], v[198:201], v[4:7]
	v_mfma_f32_16x16x32_bf16 v[0:3], v[166:169], v[198:201], v[0:3]
	v_mfma_f32_16x16x32_bf16 v[52:55], v[162:165], v[178:181], v[52:55]
	v_mfma_f32_16x16x32_bf16 v[48:51], v[170:173], v[178:181], v[48:51]
	v_mfma_f32_16x16x32_bf16 v[36:39], v[162:165], v[186:189], v[36:39]
	v_mfma_f32_16x16x32_bf16 v[32:35], v[170:173], v[186:189], v[32:35]
	v_mfma_f32_16x16x32_bf16 v[20:23], v[162:165], v[194:197], v[20:23]
	v_mfma_f32_16x16x32_bf16 v[16:19], v[170:173], v[194:197], v[16:19]
	v_mfma_f32_16x16x32_bf16 v[4:7], v[162:165], v[202:205], v[4:7]
	v_mfma_f32_16x16x32_bf16 v[0:3], v[170:173], v[202:205], v[0:3]
	s_barrier
	s_cbranch_scc1 .LBB0_1261
	s_add_i32 s82, s82, 2
	s_branch .LBB0_1257
